# v034 + P0 sample-memory K/V bf16 conversion loop with all 8 loads in flight (4 uniform iterations unrolled)
# baseline (speedup 1.0000x reference)
.LBB0_100:
	v_or_b32_e32 v1, s4, v66
	s_mov_b32 s0, 0x80000
	v_cmp_gt_i32_e32 vcc, s0, v1
	s_and_saveexec_b64 s[0:1], vcc
	s_cbranch_execz .LBB0_103
	s_mov_b64 s[22:23], 0
	s_mov_b32 s4, 0x7ffff
	s_waitcnt lgkmcnt(0)
	v_mov_b32_e32 v4, s59
	v_mov_b32_e32 v5, s57
	v_mov_b32_e32 v6, s58
	v_mov_b32_e32 v7, s56
	v_mov_b32_e32 v8, 0x2ce00000
	v_mov_b32_e32 v9, 0x2c500000
	v_mov_b32_e32 v3, 0
	s_movk_i32 s5, 0x7fff
	s_mov_b32 s6, 0xffff0000
	v_mov_b32_e32 v10, v1
	s_cmp_lg_u32 s3, 0x20000
	s_cbranch_scc1 .LBB0_102
	v_ashrrev_i32_e32 v2, 31, v10
	v_lshrrev_b32_e32 v2, 14, v2
	v_add_u32_e32 v2, v10, v2
	v_and_b32_e32 v2, 0xfffc0000, v2
	v_add_u32_e32 v11, 0x3ffff, v10
	v_sub_u32_e32 v2, v10, v2
	v_cmp_gt_u32_e32 vcc, s4, v11
	v_ashrrev_i32_e32 v11, 31, v2
	v_lshrrev_b32_e32 v11, 18, v11
	v_add_u32_e32 v11, v2, v11
	v_ashrrev_i32_e32 v20, 14, v11
	v_mul_i32_i24_e32 v11, 0x4000, v20
	v_ashrrev_i32_e32 v21, 31, v20
	v_sub_u32_e32 v22, v2, v11
	v_cndmask_b32_e32 v13, v4, v5, vcc
	v_cndmask_b32_e32 v12, v6, v7, vcc
	v_lshlrev_b64 v[14:15], 19, v[20:21]
	v_ashrrev_i32_e32 v23, 31, v22
	v_lshl_add_u64 v[12:13], v[12:13], 0, v[14:15]
	v_lshlrev_b64 v[14:15], 5, v[22:23]
	v_lshl_add_u64 v[16:17], v[12:13], 0, v[14:15]
	global_load_dwordx4 v[104:107], v[16:17], off
	global_load_dwordx4 v[108:111], v[16:17], off offset:16
	v_cndmask_b32_e32 v2, v8, v9, vcc
	v_lshl_add_u64 v[24:25], s[20:21], 0, v[2:3]
	v_lshlrev_b64 v[20:21], 18, v[20:21]
	v_lshl_add_u64 v[20:21], v[24:25], 0, v[20:21]
	v_add_u32_e32 v10, s3, v10
	v_lshl_add_u64 v[20:21], v[22:23], 4, v[20:21]
	v_add_co_u32_e32 v20, vcc, 0x80000, v20
	s_nop 1
	v_addc_co_u32_e32 v21, vcc, 0, v21, vcc
	v_mov_b32_e32 v136, v20
	v_mov_b32_e32 v137, v21
	v_ashrrev_i32_e32 v2, 31, v10
	v_lshrrev_b32_e32 v2, 14, v2
	v_add_u32_e32 v2, v10, v2
	v_and_b32_e32 v2, 0xfffc0000, v2
	v_add_u32_e32 v11, 0x3ffff, v10
	v_sub_u32_e32 v2, v10, v2
	v_cmp_gt_u32_e32 vcc, s4, v11
	v_ashrrev_i32_e32 v11, 31, v2
	v_lshrrev_b32_e32 v11, 18, v11
	v_add_u32_e32 v11, v2, v11
	v_ashrrev_i32_e32 v20, 14, v11
	v_mul_i32_i24_e32 v11, 0x4000, v20
	v_ashrrev_i32_e32 v21, 31, v20
	v_sub_u32_e32 v22, v2, v11
	v_cndmask_b32_e32 v13, v4, v5, vcc
	v_cndmask_b32_e32 v12, v6, v7, vcc
	v_lshlrev_b64 v[14:15], 19, v[20:21]
	v_ashrrev_i32_e32 v23, 31, v22
	v_lshl_add_u64 v[12:13], v[12:13], 0, v[14:15]
	v_lshlrev_b64 v[14:15], 5, v[22:23]
	v_lshl_add_u64 v[16:17], v[12:13], 0, v[14:15]
	global_load_dwordx4 v[112:115], v[16:17], off
	global_load_dwordx4 v[116:119], v[16:17], off offset:16
	v_cndmask_b32_e32 v2, v8, v9, vcc
	v_lshl_add_u64 v[24:25], s[20:21], 0, v[2:3]
	v_lshlrev_b64 v[20:21], 18, v[20:21]
	v_lshl_add_u64 v[20:21], v[24:25], 0, v[20:21]
	v_add_u32_e32 v10, s3, v10
	v_lshl_add_u64 v[20:21], v[22:23], 4, v[20:21]
	v_add_co_u32_e32 v20, vcc, 0x80000, v20
	s_nop 1
	v_addc_co_u32_e32 v21, vcc, 0, v21, vcc
	v_mov_b32_e32 v138, v20
	v_mov_b32_e32 v139, v21
	v_ashrrev_i32_e32 v2, 31, v10
	v_lshrrev_b32_e32 v2, 14, v2
	v_add_u32_e32 v2, v10, v2
	v_and_b32_e32 v2, 0xfffc0000, v2
	v_add_u32_e32 v11, 0x3ffff, v10
	v_sub_u32_e32 v2, v10, v2
	v_cmp_gt_u32_e32 vcc, s4, v11
	v_ashrrev_i32_e32 v11, 31, v2
	v_lshrrev_b32_e32 v11, 18, v11
	v_add_u32_e32 v11, v2, v11
	v_ashrrev_i32_e32 v20, 14, v11
	v_mul_i32_i24_e32 v11, 0x4000, v20
	v_ashrrev_i32_e32 v21, 31, v20
	v_sub_u32_e32 v22, v2, v11
	v_cndmask_b32_e32 v13, v4, v5, vcc
	v_cndmask_b32_e32 v12, v6, v7, vcc
	v_lshlrev_b64 v[14:15], 19, v[20:21]
	v_ashrrev_i32_e32 v23, 31, v22
	v_lshl_add_u64 v[12:13], v[12:13], 0, v[14:15]
	v_lshlrev_b64 v[14:15], 5, v[22:23]
	v_lshl_add_u64 v[16:17], v[12:13], 0, v[14:15]
	global_load_dwordx4 v[120:123], v[16:17], off
	global_load_dwordx4 v[124:127], v[16:17], off offset:16
	v_cndmask_b32_e32 v2, v8, v9, vcc
	v_lshl_add_u64 v[24:25], s[20:21], 0, v[2:3]
	v_lshlrev_b64 v[20:21], 18, v[20:21]
	v_lshl_add_u64 v[20:21], v[24:25], 0, v[20:21]
	v_add_u32_e32 v10, s3, v10
	v_lshl_add_u64 v[20:21], v[22:23], 4, v[20:21]
	v_add_co_u32_e32 v20, vcc, 0x80000, v20
	s_nop 1
	v_addc_co_u32_e32 v21, vcc, 0, v21, vcc
	v_mov_b32_e32 v140, v20
	v_mov_b32_e32 v141, v21
	v_ashrrev_i32_e32 v2, 31, v10
	v_lshrrev_b32_e32 v2, 14, v2
	v_add_u32_e32 v2, v10, v2
	v_and_b32_e32 v2, 0xfffc0000, v2
	v_add_u32_e32 v11, 0x3ffff, v10
	v_sub_u32_e32 v2, v10, v2
	v_cmp_gt_u32_e32 vcc, s4, v11
	v_ashrrev_i32_e32 v11, 31, v2
	v_lshrrev_b32_e32 v11, 18, v11
	v_add_u32_e32 v11, v2, v11
	v_ashrrev_i32_e32 v20, 14, v11
	v_mul_i32_i24_e32 v11, 0x4000, v20
	v_ashrrev_i32_e32 v21, 31, v20
	v_sub_u32_e32 v22, v2, v11
	v_cndmask_b32_e32 v13, v4, v5, vcc
	v_cndmask_b32_e32 v12, v6, v7, vcc
	v_lshlrev_b64 v[14:15], 19, v[20:21]
	v_ashrrev_i32_e32 v23, 31, v22
	v_lshl_add_u64 v[12:13], v[12:13], 0, v[14:15]
	v_lshlrev_b64 v[14:15], 5, v[22:23]
	v_lshl_add_u64 v[16:17], v[12:13], 0, v[14:15]
	global_load_dwordx4 v[128:131], v[16:17], off
	global_load_dwordx4 v[132:135], v[16:17], off offset:16
	v_cndmask_b32_e32 v2, v8, v9, vcc
	v_lshl_add_u64 v[24:25], s[20:21], 0, v[2:3]
	v_lshlrev_b64 v[20:21], 18, v[20:21]
	v_lshl_add_u64 v[20:21], v[24:25], 0, v[20:21]
	v_add_u32_e32 v10, s3, v10
	v_lshl_add_u64 v[20:21], v[22:23], 4, v[20:21]
	v_add_co_u32_e32 v20, vcc, 0x80000, v20
	s_nop 1
	v_addc_co_u32_e32 v21, vcc, 0, v21, vcc
	v_mov_b32_e32 v142, v20
	v_mov_b32_e32 v143, v21
	s_waitcnt vmcnt(6)
	v_bfe_u32 v2, v104, 16, 1
	v_bfe_u32 v22, v106, 16, 1
	v_bfe_u32 v24, v108, 16, 1
	v_bfe_u32 v26, v110, 16, 1
	v_bfe_u32 v11, v105, 16, 1
	v_bfe_u32 v23, v107, 16, 1
	v_bfe_u32 v25, v109, 16, 1
	v_bfe_u32 v27, v111, 16, 1
	v_add3_u32 v2, v104, v2, s5
	v_add3_u32 v12, v106, v22, s5
	v_add3_u32 v14, v108, v24, s5
	v_add3_u32 v16, v110, v26, s5
	v_add3_u32 v11, v105, v11, s5
	v_add3_u32 v13, v107, v23, s5
	v_add3_u32 v15, v109, v25, s5
	v_add3_u32 v17, v111, v27, s5
	v_lshrrev_b32_e32 v2, 16, v2
	v_lshrrev_b32_e32 v18, 16, v12
	v_lshrrev_b32_e32 v14, 16, v14
	v_lshrrev_b32_e32 v16, 16, v16
	v_and_or_b32 v12, v11, s6, v2
	v_and_or_b32 v13, v13, s6, v18
	v_and_or_b32 v14, v15, s6, v14
	v_and_or_b32 v15, v17, s6, v16
	global_store_dwordx4 v[136:137], v[12:15], off
	s_waitcnt vmcnt(5)
	v_bfe_u32 v2, v112, 16, 1
	v_bfe_u32 v22, v114, 16, 1
	v_bfe_u32 v24, v116, 16, 1
	v_bfe_u32 v26, v118, 16, 1
	v_bfe_u32 v11, v113, 16, 1
	v_bfe_u32 v23, v115, 16, 1
	v_bfe_u32 v25, v117, 16, 1
	v_bfe_u32 v27, v119, 16, 1
	v_add3_u32 v2, v112, v2, s5
	v_add3_u32 v12, v114, v22, s5
	v_add3_u32 v14, v116, v24, s5
	v_add3_u32 v16, v118, v26, s5
	v_add3_u32 v11, v113, v11, s5
	v_add3_u32 v13, v115, v23, s5
	v_add3_u32 v15, v117, v25, s5
	v_add3_u32 v17, v119, v27, s5
	v_lshrrev_b32_e32 v2, 16, v2
	v_lshrrev_b32_e32 v18, 16, v12
	v_lshrrev_b32_e32 v14, 16, v14
	v_lshrrev_b32_e32 v16, 16, v16
	v_and_or_b32 v12, v11, s6, v2
	v_and_or_b32 v13, v13, s6, v18
	v_and_or_b32 v14, v15, s6, v14
	v_and_or_b32 v15, v17, s6, v16
	global_store_dwordx4 v[138:139], v[12:15], off
	s_waitcnt vmcnt(4)
	v_bfe_u32 v2, v120, 16, 1
	v_bfe_u32 v22, v122, 16, 1
	v_bfe_u32 v24, v124, 16, 1
	v_bfe_u32 v26, v126, 16, 1
	v_bfe_u32 v11, v121, 16, 1
	v_bfe_u32 v23, v123, 16, 1
	v_bfe_u32 v25, v125, 16, 1
	v_bfe_u32 v27, v127, 16, 1
	v_add3_u32 v2, v120, v2, s5
	v_add3_u32 v12, v122, v22, s5
	v_add3_u32 v14, v124, v24, s5
	v_add3_u32 v16, v126, v26, s5
	v_add3_u32 v11, v121, v11, s5
	v_add3_u32 v13, v123, v23, s5
	v_add3_u32 v15, v125, v25, s5
	v_add3_u32 v17, v127, v27, s5
	v_lshrrev_b32_e32 v2, 16, v2
	v_lshrrev_b32_e32 v18, 16, v12
	v_lshrrev_b32_e32 v14, 16, v14
	v_lshrrev_b32_e32 v16, 16, v16
	v_and_or_b32 v12, v11, s6, v2
	v_and_or_b32 v13, v13, s6, v18
	v_and_or_b32 v14, v15, s6, v14
	v_and_or_b32 v15, v17, s6, v16
	global_store_dwordx4 v[140:141], v[12:15], off
	s_waitcnt vmcnt(3)
	v_bfe_u32 v2, v128, 16, 1
	v_bfe_u32 v22, v130, 16, 1
	v_bfe_u32 v24, v132, 16, 1
	v_bfe_u32 v26, v134, 16, 1
	v_bfe_u32 v11, v129, 16, 1
	v_bfe_u32 v23, v131, 16, 1
	v_bfe_u32 v25, v133, 16, 1
	v_bfe_u32 v27, v135, 16, 1
	v_add3_u32 v2, v128, v2, s5
	v_add3_u32 v12, v130, v22, s5
	v_add3_u32 v14, v132, v24, s5
	v_add3_u32 v16, v134, v26, s5
	v_add3_u32 v11, v129, v11, s5
	v_add3_u32 v13, v131, v23, s5
	v_add3_u32 v15, v133, v25, s5
	v_add3_u32 v17, v135, v27, s5
	v_lshrrev_b32_e32 v2, 16, v2
	v_lshrrev_b32_e32 v18, 16, v12
	v_lshrrev_b32_e32 v14, 16, v14
	v_lshrrev_b32_e32 v16, 16, v16
	v_and_or_b32 v12, v11, s6, v2
	v_and_or_b32 v13, v13, s6, v18
	v_and_or_b32 v14, v15, s6, v14
	v_and_or_b32 v15, v17, s6, v16
	global_store_dwordx4 v[142:143], v[12:15], off
	s_branch .LBB0_103
